# v51 + attention MODE-1 epilogue: xor-1/2/4/8 hops of the headwise rmsnorm butterfly via DPP adds instead of ds_bpermute round trips; now-redundant lgkmcnt waits dropped
# baseline (speedup 1.0000x reference)
.LBB0_749:
	s_or_b64 exec, exec, s[4:5]
	s_waitcnt lgkmcnt(0)
	ds_read_b128 v[68:71], v66 offset:128
	ds_read_b128 v[72:75], v66 offset:160
	s_mov_b64 s[6:7], s[0:1]
	s_add_u32 s4, s10, s13
	s_addc_u32 s5, s37, s14
	s_waitcnt lgkmcnt(1)
	v_rcp_f32_e32 v67, v68
	v_rcp_f32_e32 v76, v69
	v_rcp_f32_e32 v77, v70
	v_rcp_f32_e32 v78, v71
	s_waitcnt lgkmcnt(0)
	v_rcp_f32_e32 v79, v72
	ds_read_b128 v[68:71], v66 offset:192
	v_rcp_f32_e32 v80, v73
	v_rcp_f32_e32 v81, v74
	v_rcp_f32_e32 v82, v75
	ds_read_b128 v[72:75], v66 offset:224
	s_load_dwordx2 s[6:7], s[6:7], 0xa0
	s_lshl_b64 s[4:5], s[4:5], 11
	s_waitcnt lgkmcnt(0)
	v_rcp_f32_e32 v66, v68
	v_rcp_f32_e32 v68, v69
	v_rcp_f32_e32 v69, v70
	s_add_u32 s8, s6, s4
	v_rcp_f32_e32 v70, v71
	v_rcp_f32_e32 v71, v72
	v_rcp_f32_e32 v72, v73
	v_rcp_f32_e32 v73, v74
	v_rcp_f32_e32 v74, v75
	s_addc_u32 s9, s7, s5
	s_lshl_b32 s4, s12, 12
	s_add_i32 s10, s4, 0
	v_mul_f32_e32 v18, v18, v67
	v_mul_f32_e32 v50, v50, v67
	v_mul_f32_e32 v34, v34, v67
	v_mul_f32_e32 v67, v2, v67
	s_add_i32 s10, s10, 0x16800
	v_lshlrev_b32_e32 v2, 4, v1
	v_mul_f32_e32 v75, v3, v76
	s_mov_b64 s[4:5], s[0:1]
	v_and_b32_e32 v3, 0x380, v2
	v_add_u32_e32 v2, s10, v188
	v_mul_f32_e32 v89, v48, v73
	v_mul_f32_e32 v48, v65, v74
	v_add_u32_e32 v65, v2, v3
	v_mul_f32_e32 v19, v19, v76
	v_mul_f32_e32 v51, v51, v76
	v_mul_f32_e32 v35, v35, v76
	v_mul_f32_e32 v76, v4, v77
	s_load_dwordx2 s[4:5], s[4:5], 0x70
	v_lshlrev_b32_e32 v3, 1, v207
	v_lshlrev_b32_e32 v4, 9, v208
	s_waitcnt vmcnt(5)
	ds_write_b128 v65, v[138:141]
	ds_write_b128 v65, v[130:133] offset:1024
	ds_write_b128 v65, v[134:137] offset:2048
	s_waitcnt vmcnt(3)
	ds_write_b128 v65, v[142:145] offset:3072
	v_mul_f32_e32 v85, v10, v66
	v_mul_f32_e32 v10, v27, v68
	v_mul_f32_e32 v27, v59, v68
	v_mul_f32_e32 v59, v60, v69
	v_mul_f32_e32 v60, v12, v69
	v_mul_f32_e32 v12, v29, v70
	v_mul_f32_e32 v29, v61, v70
	v_mul_f32_e32 v30, v30, v71
	v_mul_f32_e32 v61, v62, v71
	v_mul_f32_e32 v86, v46, v71
	v_mul_f32_e32 v87, v14, v71
	v_add3_u32 v71, s10, v3, v4
	s_waitcnt lgkmcnt(0)
	v_mul_f32_e32 v20, v20, v77
	v_mul_f32_e32 v52, v52, v77
	v_mul_f32_e32 v36, v36, v77
	v_mul_f32_e32 v21, v21, v78
	v_mul_f32_e32 v53, v53, v78
	v_mul_f32_e32 v77, v37, v78
	v_mul_f32_e32 v78, v5, v78
	v_mul_f32_e32 v5, v22, v79
	v_mul_f32_e32 v22, v54, v79
	v_mul_f32_e32 v38, v38, v79
	v_mul_f32_e32 v79, v6, v79
	v_mul_f32_e32 v6, v23, v80
	v_mul_f32_e32 v23, v55, v80
	v_mul_f32_e32 v83, v39, v80
	v_mul_f32_e32 v80, v7, v80
	v_mul_f32_e32 v7, v24, v81
	v_mul_f32_e32 v24, v56, v81
	v_mul_f32_e32 v84, v40, v81
	v_mul_f32_e32 v81, v8, v81
	v_mul_f32_e32 v8, v25, v82
	v_mul_f32_e32 v25, v57, v82
	v_mul_f32_e32 v41, v41, v82
	v_mul_f32_e32 v57, v9, v82
	v_mul_f32_e32 v9, v26, v66
	v_mul_f32_e32 v26, v58, v66
	v_mul_f32_e32 v82, v42, v66
	v_mul_f32_e32 v28, v28, v69
	v_mul_f32_e32 v44, v44, v69
	v_mul_f32_e32 v66, v31, v72
	v_mul_f32_e32 v69, v32, v73
	v_mul_f32_e32 v90, v16, v73
	v_mul_f32_e32 v16, v33, v74
	ds_read_u16 v14, v71
	ds_read_u16 v31, v71 offset:64
	ds_read_u16 v32, v71 offset:128
	ds_read_u16 v33, v71 offset:192
	ds_read_u16 v37, v71 offset:256
	ds_read_u16 v39, v71 offset:320
	ds_read_u16 v40, v71 offset:384
	ds_read_u16 v42, v71 offset:448
	s_waitcnt lgkmcnt(0)
	v_lshlrev_b32_e32 v14, 16, v14
	v_fma_f32 v92, -v203, v18, v14
	v_lshlrev_b32_e32 v14, 16, v31
	v_fma_f32 v93, -v203, v50, v14
	v_lshlrev_b32_e32 v14, 16, v32
	v_fma_f32 v94, -v203, v19, v14
	v_lshlrev_b32_e32 v14, 16, v33
	v_fma_f32 v51, -v203, v51, v14
	v_lshlrev_b32_e32 v14, 16, v37
	v_fma_f32 v37, -v203, v20, v14
	v_lshlrev_b32_e32 v14, 16, v39
	v_fma_f32 v32, -v203, v52, v14
	v_lshlrev_b32_e32 v14, 16, v40
	v_fma_f32 v46, -v203, v21, v14
	v_lshlrev_b32_e32 v14, 16, v42
	v_fma_f32 v40, -v203, v53, v14
	ds_read_u16 v14, v71 offset:1024
	ds_read_u16 v18, v71 offset:1088
	ds_read_u16 v19, v71 offset:1152
	ds_read_u16 v20, v71 offset:1216
	ds_read_u16 v21, v71 offset:1280
	ds_read_u16 v31, v71 offset:1344
	ds_read_u16 v33, v71 offset:1408
	ds_read_u16 v39, v71 offset:1472
	s_waitcnt lgkmcnt(7)
	v_lshlrev_b32_e32 v14, 16, v14
	v_fma_f32 v55, -v203, v5, v14
	s_waitcnt lgkmcnt(6)
	v_lshlrev_b32_e32 v5, 16, v18
	v_mul_f32_e32 v91, v49, v74
	v_fma_f32 v49, -v203, v22, v5
	s_waitcnt lgkmcnt(5)
	v_lshlrev_b32_e32 v5, 16, v19
	v_mul_f32_e32 v43, v43, v68
	v_mul_f32_e32 v11, v11, v68
	v_mul_f32_e32 v68, v63, v72
	v_fma_f32 v63, -v203, v6, v5
	s_waitcnt lgkmcnt(4)
	v_lshlrev_b32_e32 v5, 16, v20
	v_fma_f32 v58, -v203, v23, v5
	s_waitcnt lgkmcnt(3)
	v_lshlrev_b32_e32 v5, 16, v21
	v_mul_f32_e32 v45, v45, v70
	v_mul_f32_e32 v13, v13, v70
	v_mul_f32_e32 v70, v64, v73
	v_fma_f32 v64, -v203, v7, v5
	s_waitcnt lgkmcnt(2)
	v_lshlrev_b32_e32 v5, 16, v31
	v_fma_f32 v62, -v203, v24, v5
	s_waitcnt lgkmcnt(1)
	v_lshlrev_b32_e32 v5, 16, v33
	v_fma_f32 v56, -v203, v8, v5
	s_waitcnt lgkmcnt(0)
	v_lshlrev_b32_e32 v5, 16, v39
	v_fma_f32 v54, -v203, v25, v5
	ds_read_u16 v5, v71 offset:2048
	ds_read_u16 v6, v71 offset:2112
	ds_read_u16 v7, v71 offset:2176
	ds_read_u16 v8, v71 offset:2240
	ds_read_u16 v14, v71 offset:2304
	ds_read_u16 v18, v71 offset:2368
	ds_read_u16 v19, v71 offset:2432
	ds_read_u16 v20, v71 offset:2496
	s_waitcnt lgkmcnt(7)
	v_lshlrev_b32_e32 v5, 16, v5
	v_fma_f32 v50, -v203, v9, v5
	s_waitcnt lgkmcnt(6)
	v_lshlrev_b32_e32 v5, 16, v6
	v_mul_f32_e32 v88, v47, v72
	v_fma_f32 v47, -v203, v26, v5
	s_waitcnt lgkmcnt(5)
	v_lshlrev_b32_e32 v5, 16, v7
	v_fma_f32 v42, -v203, v10, v5
	s_waitcnt lgkmcnt(4)
	v_lshlrev_b32_e32 v5, 16, v8
	v_fma_f32 v39, -v203, v27, v5
	s_waitcnt lgkmcnt(3)
	v_lshlrev_b32_e32 v5, 16, v14
	v_fma_f32 v33, -v203, v28, v5
	s_waitcnt lgkmcnt(2)
	v_lshlrev_b32_e32 v5, 16, v18
	v_fma_f32 v31, -v203, v59, v5
	s_waitcnt lgkmcnt(1)
	v_lshlrev_b32_e32 v5, 16, v19
	v_fma_f32 v23, -v203, v12, v5
	s_waitcnt lgkmcnt(0)
	v_lshlrev_b32_e32 v5, 16, v20
	v_fma_f32 v21, -v203, v29, v5
	ds_read_u16 v5, v71 offset:3072
	ds_read_u16 v6, v71 offset:3136
	ds_read_u16 v7, v71 offset:3200
	ds_read_u16 v8, v71 offset:3264
	ds_read_u16 v18, v71 offset:3328
	ds_read_u16 v19, v71 offset:3392
	ds_read_u16 v20, v71 offset:3456
	ds_read_u16 v22, v71 offset:3520
	s_waitcnt lgkmcnt(7)
	v_lshlrev_b32_e32 v5, 16, v5
	v_fma_f32 v14, -v203, v30, v5
	s_waitcnt lgkmcnt(6)
	v_lshlrev_b32_e32 v5, 16, v6
	v_fma_f32 v12, -v203, v61, v5
	s_waitcnt lgkmcnt(5)
	v_lshlrev_b32_e32 v5, 16, v7
	v_fma_f32 v9, -v203, v66, v5
	s_waitcnt lgkmcnt(4)
	v_lshlrev_b32_e32 v5, 16, v8
	v_fma_f32 v10, -v203, v68, v5
	s_waitcnt lgkmcnt(3)
	v_lshlrev_b32_e32 v5, 16, v18
	v_fma_f32 v8, -v203, v69, v5
	s_waitcnt lgkmcnt(2)
	v_lshlrev_b32_e32 v5, 16, v19
	s_waitcnt lgkmcnt(0)
	ds_write_b128 v65, v[114:117]
	s_waitcnt vmcnt(2)
	ds_write_b128 v65, v[118:121] offset:1024
	s_waitcnt vmcnt(1)
	ds_write_b128 v65, v[122:125] offset:2048
	s_waitcnt vmcnt(0)
	ds_write_b128 v65, v[126:129] offset:3072
	v_fma_f32 v7, -v203, v70, v5
	s_waitcnt lgkmcnt(5)
	v_lshlrev_b32_e32 v5, 16, v20
	s_waitcnt lgkmcnt(0)
	v_fma_f32 v5, -v203, v16, v5
	s_waitcnt lgkmcnt(4)
	v_lshlrev_b32_e32 v6, 16, v22
	ds_read_u16 v16, v71
	ds_read_u16 v18, v71 offset:64
	ds_read_u16 v19, v71 offset:128
	ds_read_u16 v20, v71 offset:192
	ds_read_u16 v22, v71 offset:256
	ds_read_u16 v24, v71 offset:320
	ds_read_u16 v25, v71 offset:384
	ds_read_u16 v26, v71 offset:448
	s_waitcnt lgkmcnt(7)
	v_lshlrev_b32_e32 v16, 16, v16
	v_fma_f32 v29, -v203, v34, v16
	s_waitcnt lgkmcnt(6)
	v_lshlrev_b32_e32 v16, 16, v18
	v_fma_f32 v52, -v203, v67, v16
	s_waitcnt lgkmcnt(5)
	v_lshlrev_b32_e32 v16, 16, v19
	v_fma_f32 v59, -v203, v35, v16
	s_waitcnt lgkmcnt(4)
	v_lshlrev_b32_e32 v16, 16, v20
	v_fma_f32 v6, -v203, v48, v6
	v_fma_f32 v67, -v203, v75, v16
	ds_read_u16 v16, v71 offset:1024
	ds_read_u16 v18, v71 offset:1088
	ds_read_u16 v19, v71 offset:1152
	ds_read_u16 v20, v71 offset:1216
	ds_read_u16 v27, v71 offset:1280
	ds_read_u16 v28, v71 offset:1344
	ds_read_u16 v30, v71 offset:1408
	ds_read_u16 v34, v71 offset:1472
	ds_read_u16 v35, v71 offset:2048
	ds_read_u16 v48, v71 offset:2112
	ds_read_u16 v53, v71 offset:2176
	ds_read_u16 v75, v71 offset:2240
	ds_read_u16 v95, v71 offset:2304
	ds_read_u16 v96, v71 offset:2368
	ds_read_u16 v97, v71 offset:2432
	ds_read_u16 v98, v71 offset:2496
	ds_read_u16 v99, v71 offset:3072
	ds_read_u16 v100, v71 offset:3136
	ds_read_u16 v101, v71 offset:3200
	ds_read_u16 v102, v71 offset:3264
	ds_read_u16 v103, v71 offset:3328
	ds_read_u16 v104, v71 offset:3392
	ds_read_u16 v105, v71 offset:3456
	ds_read_u16 v106, v71 offset:3520
	s_waitcnt lgkmcnt(14)
	v_lshlrev_b32_e32 v22, 16, v22
	v_fma_f32 v109, -v203, v36, v22
	v_lshlrev_b32_e32 v22, 16, v24
	v_lshlrev_b32_e32 v16, 16, v16
	v_fma_f32 v76, -v203, v76, v22
	v_lshlrev_b32_e32 v22, 16, v25
	v_fma_f32 v110, -v203, v38, v16
	v_lshlrev_b32_e32 v16, 16, v18
	s_waitcnt lgkmcnt(0)
	v_lshlrev_b32_e32 v61, 2, v207
	v_fma_f32 v77, -v203, v77, v22
	v_lshlrev_b32_e32 v22, 16, v26
	v_fma_f32 v66, -v203, v79, v16
	v_lshlrev_b32_e32 v16, 16, v19
	global_load_dword v107, v61, s[4:5]
	global_load_dword v108, v61, s[4:5] offset:128
	v_fma_f32 v78, -v203, v78, v22
	v_fma_f32 v71, -v203, v83, v16
	v_lshlrev_b32_e32 v16, 16, v20
	global_load_dword v20, v61, s[4:5] offset:256
	global_load_dword v22, v61, s[4:5] offset:384
	v_fma_f32 v70, -v203, v80, v16
	v_lshlrev_b32_e32 v16, 16, v27
	v_mul_f32_e32 v17, v17, v74
	v_fma_f32 v74, -v203, v84, v16
	v_lshlrev_b32_e32 v16, 16, v28
	v_fma_f32 v73, -v203, v81, v16
	v_lshlrev_b32_e32 v16, 16, v30
	v_mul_f32_e32 v15, v15, v72
	v_fma_f32 v72, -v203, v41, v16
	v_lshlrev_b32_e32 v16, 16, v34
	v_fma_f32 v69, -v203, v57, v16
	v_lshlrev_b32_e32 v16, 16, v35
	v_fma_f32 v68, -v203, v82, v16
	v_lshlrev_b32_e32 v16, 16, v48
	v_fma_f32 v65, -v203, v85, v16
	s_waitcnt lgkmcnt(13)
	v_lshlrev_b32_e32 v16, 16, v53
	v_fma_f32 v61, -v203, v43, v16
	s_waitcnt lgkmcnt(12)
	v_lshlrev_b32_e32 v16, 16, v75
	v_fma_f32 v57, -v203, v11, v16
	v_mul_f32_e32 v16, v93, v93
	v_mul_f32_e32 v18, v52, v52
	v_fmac_f32_e32 v16, v92, v92
	v_fmac_f32_e32 v18, v29, v29
	v_add_f32_e32 v16, v16, v18
	s_waitcnt lgkmcnt(12)
	v_lshlrev_b32_e32 v11, 16, v95
	v_fma_f32 v53, -v203, v44, v11
	s_waitcnt lgkmcnt(11)
	v_lshlrev_b32_e32 v11, 16, v96
	v_fma_f32 v48, -v203, v60, v11
	s_waitcnt lgkmcnt(0)
	v_add_f32_dpp v16, v16, v16 quad_perm:[1,0,3,2] row_mask:0xf bank_mask:0xf
	v_lshlrev_b32_e32 v11, 16, v97
	v_fma_f32 v45, -v203, v45, v11
	v_lshlrev_b32_e32 v11, 16, v98
	v_fma_f32 v41, -v203, v13, v11
	s_waitcnt lgkmcnt(0)
	v_add_f32_dpp v13, v16, v16 quad_perm:[2,3,0,1] row_mask:0xf bank_mask:0xf
	v_lshlrev_b32_e32 v11, 16, v99
	v_fma_f32 v38, -v203, v86, v11
	v_lshlrev_b32_e32 v11, 16, v100
	v_fma_f32 v34, -v203, v87, v11
	v_add_f32_dpp v13, v13, v13 row_half_mirror row_mask:0xf bank_mask:0xf
	v_lshlrev_b32_e32 v11, 16, v101
	v_fma_f32 v30, -v203, v88, v11
	v_lshlrev_b32_e32 v11, 16, v102
	v_fma_f32 v24, -v203, v15, v11
	v_add_f32_dpp v15, v13, v13 row_mirror row_mask:0xf bank_mask:0xf
	ds_bpermute_b32 v18, v196, v15
	v_lshlrev_b32_e32 v11, 16, v103
	v_fma_f32 v16, -v203, v89, v11
	v_lshlrev_b32_e32 v11, 16, v104
	v_fma_f32 v19, -v203, v90, v11
	s_waitcnt lgkmcnt(0)
	v_add_f32_e32 v15, v15, v18
	v_fmamk_f32 v15, v15, 0x3c000000, v204
	v_rsq_f32_e32 v224, v15
	v_lshlrev_b32_e32 v11, 16, v105
	v_fma_f32 v13, -v203, v91, v11
	v_lshlrev_b32_e32 v11, 16, v106
	v_fma_f32 v15, -v203, v17, v11
	v_lshrrev_b32_e32 v1, 3, v1
	v_mov_b32_e32 v189, v146
	s_waitcnt vmcnt(3)
	v_mul_f32_e32 v18, 0x3f24fd5c, v107
	v_mul_f32_e32 v26, v51, v51
	v_mul_f32_e32 v27, v67, v67
	v_fmac_f32_e32 v26, v94, v94
	v_fmac_f32_e32 v27, v59, v59
	v_add_f32_e32 v26, v26, v27
	s_waitcnt vmcnt(2)
	v_mul_f32_e32 v17, 0x3f24fd5c, v108
	s_nop 0
	v_add_f32_dpp v27, v26, v26 quad_perm:[1,0,3,2] row_mask:0xf bank_mask:0xf
	s_waitcnt vmcnt(1)
	v_mul_f32_e32 v26, 0x3f24fd5c, v20
	s_waitcnt vmcnt(0)
	v_mul_f32_e32 v25, 0x3f24fd5c, v22
	v_add_f32_dpp v20, v27, v27 quad_perm:[2,3,0,1] row_mask:0xf bank_mask:0xf
	s_nop 1
	v_add_f32_dpp v20, v20, v20 row_half_mirror row_mask:0xf bank_mask:0xf
	v_mov_b32_e32 v35, v224
	s_nop 0
	v_add_f32_dpp v20, v20, v20 row_mirror row_mask:0xf bank_mask:0xf
	ds_bpermute_b32 v22, v196, v20
	v_mul_f32_e32 v11, v18, v35
	v_mul_f32_e32 v27, v92, v11
	v_mul_f32_e32 v11, v17, v35
	v_mul_f32_e32 v28, v93, v11
	s_waitcnt lgkmcnt(0)
	v_add_f32_e32 v20, v20, v22
	v_fmamk_f32 v20, v20, 0x3c000000, v204
	v_rsq_f32_e32 v225, v20
	v_mul_f32_e32 v11, v26, v35
	v_mul_f32_e32 v11, v29, v11
	v_mul_f32_e32 v29, v32, v32
	v_mul_f32_e32 v36, v76, v76
	v_fmac_f32_e32 v29, v37, v37
	v_fmac_f32_e32 v36, v109, v109
	v_add_f32_e32 v29, v29, v36
	s_nop 1
	v_add_f32_dpp v29, v29, v29 quad_perm:[1,0,3,2] row_mask:0xf bank_mask:0xf
	v_mul_f32_e32 v20, v25, v35
	v_mul_f32_e32 v20, v52, v20
	v_add_f32_dpp v29, v29, v29 quad_perm:[2,3,0,1] row_mask:0xf bank_mask:0xf
	s_nop 1
	v_add_f32_dpp v29, v29, v29 row_half_mirror row_mask:0xf bank_mask:0xf
	v_mov_b32_e32 v44, v225
	s_nop 0
	v_add_f32_dpp v29, v29, v29 row_mirror row_mask:0xf bank_mask:0xf
	ds_bpermute_b32 v43, v196, v29
	v_mul_f32_e32 v22, v18, v44
	v_mul_f32_e32 v35, v94, v22
	v_mul_f32_e32 v22, v17, v44
	s_waitcnt lgkmcnt(0)
	v_add_f32_e32 v29, v29, v43
	v_fmamk_f32 v29, v29, 0x3c000000, v204
	v_rsq_f32_e32 v226, v29
	v_mul_f32_e32 v36, v51, v22
	v_mul_f32_e32 v22, v26, v44
	v_mul_f32_e32 v22, v59, v22
	v_mul_f32_e32 v51, v40, v40
	v_mul_f32_e32 v52, v78, v78
	v_fmac_f32_e32 v51, v46, v46
	v_fmac_f32_e32 v52, v77, v77
	v_add_f32_e32 v51, v51, v52
	s_nop 1
	v_add_f32_dpp v51, v51, v51 quad_perm:[1,0,3,2] row_mask:0xf bank_mask:0xf
	v_mul_f32_e32 v29, v25, v44
	v_mul_f32_e32 v29, v67, v29
	v_add_f32_dpp v44, v51, v51 quad_perm:[2,3,0,1] row_mask:0xf bank_mask:0xf
	s_nop 1
	v_add_f32_dpp v44, v44, v44 row_half_mirror row_mask:0xf bank_mask:0xf
	v_mov_b32_e32 v52, v226
	s_nop 0
	v_add_f32_dpp v44, v44, v44 row_mirror row_mask:0xf bank_mask:0xf
	ds_bpermute_b32 v51, v196, v44
	v_mul_f32_e32 v43, v18, v52
	v_mul_f32_e32 v43, v37, v43
	v_mul_f32_e32 v37, v17, v52
	s_waitcnt lgkmcnt(0)
	v_add_f32_e32 v44, v44, v51
	v_fmamk_f32 v44, v44, 0x3c000000, v204
	v_rsq_f32_e32 v227, v44
	v_mul_f32_e32 v44, v32, v37
	v_mul_f32_e32 v32, v26, v52
	v_mul_f32_e32 v32, v109, v32
	v_mul_f32_e32 v59, v49, v49
	v_mul_f32_e32 v60, v66, v66
	v_fmac_f32_e32 v59, v55, v55
	v_fmac_f32_e32 v60, v110, v110
	v_add_f32_e32 v59, v59, v60
	s_nop 1
	v_add_f32_dpp v59, v59, v59 quad_perm:[1,0,3,2] row_mask:0xf bank_mask:0xf
	v_mul_f32_e32 v37, v25, v52
	v_mul_f32_e32 v37, v76, v37
	v_add_f32_dpp v52, v59, v59 quad_perm:[2,3,0,1] row_mask:0xf bank_mask:0xf
	s_nop 1
	v_add_f32_dpp v52, v52, v52 row_half_mirror row_mask:0xf bank_mask:0xf
	v_mov_b32_e32 v60, v227
	s_nop 0
	v_add_f32_dpp v52, v52, v52 row_mirror row_mask:0xf bank_mask:0xf
	ds_bpermute_b32 v59, v196, v52
	v_mul_f32_e32 v51, v18, v60
	v_mul_f32_e32 v51, v46, v51
	v_mul_f32_e32 v46, v17, v60
	s_waitcnt lgkmcnt(0)
	v_add_f32_e32 v52, v52, v59
	v_fmamk_f32 v52, v52, 0x3c000000, v204
	v_rsq_f32_e32 v228, v52
	v_mul_f32_e32 v52, v40, v46
	v_mul_f32_e32 v40, v26, v60
	v_mul_f32_e32 v40, v77, v40
	v_mul_f32_e32 v67, v58, v58
	v_mul_f32_e32 v75, v70, v70
	v_fmac_f32_e32 v67, v63, v63
	v_fmac_f32_e32 v75, v71, v71
	v_add_f32_e32 v67, v67, v75
	s_nop 1
	v_add_f32_dpp v67, v67, v67 quad_perm:[1,0,3,2] row_mask:0xf bank_mask:0xf
	v_mul_f32_e32 v46, v25, v60
	v_mul_f32_e32 v46, v78, v46
	v_add_f32_dpp v60, v67, v67 quad_perm:[2,3,0,1] row_mask:0xf bank_mask:0xf
	s_nop 1
	v_add_f32_dpp v60, v60, v60 row_half_mirror row_mask:0xf bank_mask:0xf
	v_mov_b32_e32 v75, v228
	s_nop 0
	v_add_f32_dpp v60, v60, v60 row_mirror row_mask:0xf bank_mask:0xf
	ds_bpermute_b32 v67, v196, v60
	v_mul_f32_e32 v59, v18, v75
	v_mul_f32_e32 v59, v55, v59
	v_mul_f32_e32 v55, v17, v75
	s_waitcnt lgkmcnt(0)
	v_add_f32_e32 v60, v60, v67
	v_fmamk_f32 v60, v60, 0x3c000000, v204
	v_rsq_f32_e32 v229, v60
	v_mul_f32_e32 v60, v49, v55
	v_mul_f32_e32 v49, v26, v75
	v_mul_f32_e32 v49, v110, v49
	v_mul_f32_e32 v76, v62, v62
	v_mul_f32_e32 v77, v73, v73
	v_fmac_f32_e32 v76, v64, v64
	v_fmac_f32_e32 v77, v74, v74
	v_add_f32_e32 v76, v76, v77
	s_nop 1
	v_add_f32_dpp v76, v76, v76 quad_perm:[1,0,3,2] row_mask:0xf bank_mask:0xf
	v_mul_f32_e32 v55, v25, v75
	v_mul_f32_e32 v55, v66, v55
	v_add_f32_dpp v66, v76, v76 quad_perm:[2,3,0,1] row_mask:0xf bank_mask:0xf
	s_nop 1
	v_add_f32_dpp v66, v66, v66 row_half_mirror row_mask:0xf bank_mask:0xf
	v_mov_b32_e32 v76, v229
	s_nop 0
	v_add_f32_dpp v75, v66, v66 row_mirror row_mask:0xf bank_mask:0xf
	ds_bpermute_b32 v77, v196, v75
	v_mul_f32_e32 v66, v18, v76
	v_mul_f32_e32 v66, v63, v66
	v_mul_f32_e32 v63, v17, v76
	s_waitcnt lgkmcnt(0)
	v_add_f32_e32 v67, v75, v77
	v_fmamk_f32 v67, v67, 0x3c000000, v204
	v_rsq_f32_e32 v230, v67
	v_mul_f32_e32 v67, v58, v63
	v_mul_f32_e32 v58, v26, v76
	v_mul_f32_e32 v58, v71, v58
	v_mul_f32_e32 v77, v69, v69
	v_fmac_f32_e32 v77, v72, v72
	v_mul_f32_e32 v71, v54, v54
	v_fmac_f32_e32 v71, v56, v56
	v_add_f32_e32 v71, v71, v77
	s_nop 1
	v_add_f32_dpp v71, v71, v71 quad_perm:[1,0,3,2] row_mask:0xf bank_mask:0xf
	v_mul_f32_e32 v63, v25, v76
	v_mul_f32_e32 v63, v70, v63
	v_add_f32_dpp v70, v71, v71 quad_perm:[2,3,0,1] row_mask:0xf bank_mask:0xf
	s_nop 1
	v_add_f32_dpp v70, v70, v70 row_half_mirror row_mask:0xf bank_mask:0xf
	v_mov_b32_e32 v75, v230
	s_nop 0
	v_add_f32_dpp v71, v70, v70 row_mirror row_mask:0xf bank_mask:0xf
	ds_bpermute_b32 v77, v196, v71
	v_mul_f32_e32 v70, v18, v75
	v_mul_f32_e32 v70, v64, v70
	v_mul_f32_e32 v64, v17, v75
	s_waitcnt lgkmcnt(0)
	v_add_f32_e32 v71, v71, v77
	v_fmamk_f32 v71, v71, 0x3c000000, v204
	v_rsq_f32_e32 v231, v71
	v_mul_f32_e32 v71, v62, v64
	v_mul_f32_e32 v62, v26, v75
	v_mul_f32_e32 v62, v74, v62
	v_mul_f32_e32 v77, v65, v65
	v_fmac_f32_e32 v77, v68, v68
	v_mul_f32_e32 v74, v47, v47
	v_fmac_f32_e32 v74, v50, v50
	v_add_f32_e32 v74, v74, v77
	s_nop 1
	v_add_f32_dpp v74, v74, v74 quad_perm:[1,0,3,2] row_mask:0xf bank_mask:0xf
	v_mul_f32_e32 v64, v25, v75
	v_mul_f32_e32 v64, v73, v64
	v_add_f32_dpp v73, v74, v74 quad_perm:[2,3,0,1] row_mask:0xf bank_mask:0xf
	s_nop 1
	v_add_f32_dpp v73, v73, v73 row_half_mirror row_mask:0xf bank_mask:0xf
	v_mov_b32_e32 v75, v231
	s_nop 0
	v_add_f32_dpp v74, v73, v73 row_mirror row_mask:0xf bank_mask:0xf
	ds_bpermute_b32 v77, v196, v74
	v_mul_f32_e32 v73, v18, v75
	v_mul_f32_e32 v73, v56, v73
	v_mul_f32_e32 v56, v17, v75
	s_waitcnt lgkmcnt(0)
	v_add_f32_e32 v74, v74, v77
	v_fmamk_f32 v74, v74, 0x3c000000, v204
	v_rsq_f32_e32 v224, v74
	v_mul_f32_e32 v74, v54, v56
	v_mul_f32_e32 v54, v26, v75
	v_mul_f32_e32 v54, v72, v54
	v_mul_f32_e32 v77, v57, v57
	v_fmac_f32_e32 v77, v61, v61
	v_mul_f32_e32 v72, v39, v39
	v_fmac_f32_e32 v72, v42, v42
	v_add_f32_e32 v72, v72, v77
	s_nop 1
	v_add_f32_dpp v72, v72, v72 quad_perm:[1,0,3,2] row_mask:0xf bank_mask:0xf
	v_mul_f32_e32 v56, v25, v75
	v_mul_f32_e32 v56, v69, v56
	v_add_f32_dpp v69, v72, v72 quad_perm:[2,3,0,1] row_mask:0xf bank_mask:0xf
	s_nop 1
	v_add_f32_dpp v69, v69, v69 row_half_mirror row_mask:0xf bank_mask:0xf
	v_mov_b32_e32 v75, v224
	s_nop 0
	v_add_f32_dpp v72, v69, v69 row_mirror row_mask:0xf bank_mask:0xf
	ds_bpermute_b32 v77, v196, v72
	v_mul_f32_e32 v69, v18, v75
	v_mul_f32_e32 v69, v50, v69
	v_mul_f32_e32 v50, v17, v75
	s_waitcnt lgkmcnt(0)
	v_add_f32_e32 v72, v72, v77
	v_fmamk_f32 v72, v72, 0x3c000000, v204
	v_rsq_f32_e32 v225, v72
	v_mul_f32_e32 v72, v47, v50
	v_mul_f32_e32 v47, v26, v75
	v_mul_f32_e32 v47, v68, v47
	v_mul_f32_e32 v77, v48, v48
	v_fmac_f32_e32 v77, v53, v53
	v_mul_f32_e32 v68, v31, v31
	v_fmac_f32_e32 v68, v33, v33
	v_add_f32_e32 v68, v68, v77
	s_nop 1
	v_add_f32_dpp v68, v68, v68 quad_perm:[1,0,3,2] row_mask:0xf bank_mask:0xf
	v_mul_f32_e32 v50, v25, v75
	v_mul_f32_e32 v50, v65, v50
	v_add_f32_dpp v65, v68, v68 quad_perm:[2,3,0,1] row_mask:0xf bank_mask:0xf
	s_nop 1
	v_add_f32_dpp v65, v65, v65 row_half_mirror row_mask:0xf bank_mask:0xf
	v_mov_b32_e32 v75, v225
	s_nop 0
	v_add_f32_dpp v65, v65, v65 row_mirror row_mask:0xf bank_mask:0xf
	ds_bpermute_b32 v68, v196, v65
	v_mul_f32_e32 v76, v18, v75
	v_mul_f32_e32 v76, v42, v76
	v_mul_f32_e32 v42, v17, v75
	v_mul_f32_e32 v77, v39, v42
	s_waitcnt lgkmcnt(0)
	v_add_f32_e32 v65, v65, v68
	v_fmamk_f32 v65, v65, 0x3c000000, v204
	v_mul_f32_e32 v39, v26, v75
	v_mul_f32_e32 v39, v61, v39
	v_mul_f32_e32 v68, v41, v41
	v_fmac_f32_e32 v68, v45, v45
	v_mul_f32_e32 v61, v21, v21
	v_fmac_f32_e32 v61, v23, v23
	v_add_f32_e32 v61, v61, v68
	s_nop 1
	v_add_f32_dpp v61, v61, v61 quad_perm:[1,0,3,2] row_mask:0xf bank_mask:0xf
	v_mul_f32_e32 v42, v25, v75
	v_mul_f32_e32 v42, v57, v42
	v_add_f32_dpp v57, v61, v61 quad_perm:[2,3,0,1] row_mask:0xf bank_mask:0xf
	s_nop 1
	v_add_f32_dpp v57, v57, v57 row_half_mirror row_mask:0xf bank_mask:0xf
	v_rsq_f32_e32 v65, v65
	s_nop 0
	v_add_f32_dpp v57, v57, v57 row_mirror row_mask:0xf bank_mask:0xf
	ds_bpermute_b32 v61, v196, v57
	v_mul_f32_e32 v68, v18, v65
	v_mul_f32_e32 v33, v33, v68
	v_mul_f32_e32 v68, v17, v65
	v_mul_f32_e32 v31, v31, v68
	s_waitcnt lgkmcnt(0)
	v_add_f32_e32 v57, v57, v61
	v_fmamk_f32 v57, v57, 0x3c000000, v204
	v_mul_f32_e32 v68, v26, v65
	v_mul_f32_e32 v53, v53, v68
	v_mul_f32_e32 v65, v25, v65
	v_mul_f32_e32 v48, v48, v65
	v_mul_f32_e32 v68, v12, v12
	v_mul_f32_e32 v75, v34, v34
	v_fmac_f32_e32 v68, v14, v14
	v_fmac_f32_e32 v75, v38, v38
	v_add_f32_e32 v68, v68, v75
	s_nop 1
	v_add_f32_dpp v68, v68, v68 quad_perm:[1,0,3,2] row_mask:0xf bank_mask:0xf
	s_nop 1
	v_add_f32_dpp v65, v68, v68 quad_perm:[2,3,0,1] row_mask:0xf bank_mask:0xf
	s_nop 1
	v_add_f32_dpp v65, v65, v65 row_half_mirror row_mask:0xf bank_mask:0xf
	v_rsq_f32_e32 v57, v57
	s_nop 0
	v_add_f32_dpp v65, v65, v65 row_mirror row_mask:0xf bank_mask:0xf
	ds_bpermute_b32 v68, v196, v65
	v_mul_f32_e32 v61, v18, v57
	v_mul_f32_e32 v23, v23, v61
	v_mul_f32_e32 v61, v17, v57
	v_mul_f32_e32 v21, v21, v61
	s_waitcnt lgkmcnt(0)
	v_add_f32_e32 v65, v65, v68
	v_fmamk_f32 v65, v65, 0x3c000000, v204
	v_mul_f32_e32 v61, v26, v57
	v_mul_f32_e32 v45, v45, v61
	v_mul_f32_e32 v57, v25, v57
	v_mul_f32_e32 v41, v41, v57
	v_mul_f32_e32 v68, v10, v10
	v_mul_f32_e32 v75, v24, v24
	v_fmac_f32_e32 v68, v9, v9
	v_fmac_f32_e32 v75, v30, v30
	v_add_f32_e32 v68, v68, v75
	s_nop 1
	v_add_f32_dpp v68, v68, v68 quad_perm:[1,0,3,2] row_mask:0xf bank_mask:0xf
	s_nop 1
	v_add_f32_dpp v57, v68, v68 quad_perm:[2,3,0,1] row_mask:0xf bank_mask:0xf
	s_nop 1
	v_add_f32_dpp v57, v57, v57 row_half_mirror row_mask:0xf bank_mask:0xf
	v_rsq_f32_e32 v61, v65
	s_nop 0
	v_add_f32_dpp v57, v57, v57 row_mirror row_mask:0xf bank_mask:0xf
	ds_bpermute_b32 v68, v196, v57
	v_mul_f32_e32 v65, v18, v61
	v_mul_f32_e32 v14, v14, v65
	v_mul_f32_e32 v65, v17, v61
	v_mul_f32_e32 v12, v12, v65
	s_waitcnt lgkmcnt(0)
	v_add_f32_e32 v57, v57, v68
	v_fmamk_f32 v57, v57, 0x3c000000, v204
	v_mul_f32_e32 v65, v26, v61
	v_mul_f32_e32 v38, v38, v65
	v_mul_f32_e32 v61, v25, v61
	v_mul_f32_e32 v34, v34, v61
	v_mul_f32_e32 v68, v7, v7
	v_mul_f32_e32 v75, v19, v19
	v_fmac_f32_e32 v68, v8, v8
	v_fmac_f32_e32 v75, v16, v16
	v_add_f32_e32 v68, v68, v75
	s_nop 1
	v_add_f32_dpp v68, v68, v68 quad_perm:[1,0,3,2] row_mask:0xf bank_mask:0xf
	s_nop 1
	v_add_f32_dpp v61, v68, v68 quad_perm:[2,3,0,1] row_mask:0xf bank_mask:0xf
	s_nop 1
	v_add_f32_dpp v61, v61, v61 row_half_mirror row_mask:0xf bank_mask:0xf
	v_rsq_f32_e32 v57, v57
	s_nop 0
	v_add_f32_dpp v61, v61, v61 row_mirror row_mask:0xf bank_mask:0xf
	ds_bpermute_b32 v65, v196, v61
	v_mul_f32_e32 v68, v18, v57
	v_mul_f32_e32 v68, v9, v68
	v_mul_f32_e32 v9, v17, v57
	v_mul_f32_e32 v10, v10, v9
	s_waitcnt lgkmcnt(0)
	v_add_f32_e32 v9, v61, v65
	v_fmamk_f32 v9, v9, 0x3c000000, v204
	v_mul_f32_e32 v65, v26, v57
	v_mul_f32_e32 v65, v30, v65
	v_mul_f32_e32 v30, v25, v57
	v_mul_f32_e32 v79, v24, v30
	v_mul_f32_e32 v61, v6, v6
	v_fmac_f32_e32 v61, v5, v5
	v_mul_f32_e32 v75, v15, v15
	v_fmac_f32_e32 v75, v13, v13
	v_add_f32_e32 v61, v61, v75
	s_nop 1
	v_add_f32_dpp v57, v61, v61 quad_perm:[1,0,3,2] row_mask:0xf bank_mask:0xf
	s_nop 1
	v_add_f32_dpp v24, v57, v57 quad_perm:[2,3,0,1] row_mask:0xf bank_mask:0xf
	s_nop 1
	v_add_f32_dpp v24, v24, v24 row_half_mirror row_mask:0xf bank_mask:0xf
	s_nop 1
	v_add_f32_dpp v24, v24, v24 row_mirror row_mask:0xf bank_mask:0xf
	ds_bpermute_b32 v30, v196, v24
	v_rsq_f32_e32 v9, v9
	s_nop 0
	v_mul_f32_e32 v57, v18, v9
	v_mul_f32_e32 v57, v8, v57
	s_waitcnt lgkmcnt(0)
	v_add_f32_e32 v8, v24, v30
	v_fmamk_f32 v8, v8, 0x3c000000, v204
	v_add3_u32 v78, s10, v4, v3
	v_cvt_pk_bf16_f32 v3, v27, s0
	ds_write_b16 v78, v3
	v_cvt_pk_bf16_f32 v3, v28, s0
	ds_write_b16 v78, v3 offset:64
	v_cvt_pk_bf16_f32 v3, v35, s0
	ds_write_b16 v78, v3 offset:128
	v_cvt_pk_bf16_f32 v3, v36, s0
	ds_write_b16 v78, v3 offset:192
	v_cvt_pk_bf16_f32 v3, v43, s0
	ds_write_b16 v78, v3 offset:256
	v_cvt_pk_bf16_f32 v3, v44, s0
	ds_write_b16 v78, v3 offset:320
	v_cvt_pk_bf16_f32 v3, v51, s0
	ds_write_b16 v78, v3 offset:384
	v_cvt_pk_bf16_f32 v3, v52, s0
	ds_write_b16 v78, v3 offset:448
	v_cvt_pk_bf16_f32 v3, v59, s0
	ds_write_b16 v78, v3 offset:1024
	v_cvt_pk_bf16_f32 v3, v60, s0
	ds_write_b16 v78, v3 offset:1088
	v_cvt_pk_bf16_f32 v3, v66, s0
	ds_write_b16 v78, v3 offset:1152
	v_cvt_pk_bf16_f32 v3, v67, s0
	ds_write_b16 v78, v3 offset:1216
	v_cvt_pk_bf16_f32 v3, v70, s0
	ds_write_b16 v78, v3 offset:1280
	v_cvt_pk_bf16_f32 v3, v71, s0
	ds_write_b16 v78, v3 offset:1344
	v_cvt_pk_bf16_f32 v3, v73, s0
	ds_write_b16 v78, v3 offset:1408
	v_cvt_pk_bf16_f32 v3, v74, s0
	ds_write_b16 v78, v3 offset:1472
	v_cvt_pk_bf16_f32 v3, v69, s0
	ds_write_b16 v78, v3 offset:2048
	v_cvt_pk_bf16_f32 v3, v72, s0
	v_mul_f32_e32 v30, v17, v9
	ds_write_b16 v78, v3 offset:2112
	v_cvt_pk_bf16_f32 v3, v76, s0
	v_mul_f32_e32 v7, v7, v30
	v_mul_f32_e32 v30, v26, v9
	v_mul_f32_e32 v9, v25, v9
	ds_write_b16 v78, v3 offset:2176
	v_cvt_pk_bf16_f32 v3, v77, s0
	v_mul_f32_e32 v75, v19, v9
	ds_write_b16 v78, v3 offset:2240
	v_cvt_pk_bf16_f32 v3, v33, s0
	ds_write_b16 v78, v3 offset:2304
	v_cvt_pk_bf16_f32 v3, v31, s0
	ds_write_b16 v78, v3 offset:2368
	v_cvt_pk_bf16_f32 v3, v23, s0
	v_mul_f32_e32 v16, v16, v30
	ds_write_b16 v78, v3 offset:2432
	v_cvt_pk_bf16_f32 v3, v21, s0
	ds_write_b16 v78, v3 offset:2496
	v_cvt_pk_bf16_f32 v3, v14, s0
	ds_write_b16 v78, v3 offset:3072
	v_cvt_pk_bf16_f32 v3, v12, s0
	ds_write_b16 v78, v3 offset:3136
	v_cvt_pk_bf16_f32 v3, v68, s0
	v_rsq_f32_e32 v8, v8
	ds_write_b16 v78, v3 offset:3200
	v_cvt_pk_bf16_f32 v3, v10, s0
	v_mul_f32_e32 v9, v18, v8
	ds_write_b16 v78, v3 offset:3264
	v_cvt_pk_bf16_f32 v3, v57, s0
	v_mul_f32_e32 v18, v5, v9
	v_mul_f32_e32 v5, v17, v8
	ds_write_b16 v78, v3 offset:3328
	v_cvt_pk_bf16_f32 v3, v7, s0
	v_mul_f32_e32 v6, v6, v5
	ds_write_b16 v78, v3 offset:3392
	v_cvt_pk_bf16_f32 v3, v18, s0
	v_mul_f32_e32 v5, v26, v8
	s_add_u32 s4, s8, s64
	ds_write_b16 v78, v3 offset:3456
	v_cvt_pk_bf16_f32 v3, v6, s0
	v_mul_f32_e32 v17, v13, v5
	v_mul_f32_e32 v5, v25, v8
	s_addc_u32 s5, s9, s65
	ds_write_b16 v78, v3 offset:3520
	v_mul_f32_e32 v61, v15, v5
	v_lshl_add_u64 v[4:5], s[4:5], 0, v[188:189]
	s_mov_b64 s[4:5], 0x18800000
	v_lshl_add_u32 v80, v1, 7, v2
	s_waitcnt lgkmcnt(0)
	v_lshl_add_u64 v[8:9], v[4:5], 0, s[4:5]
	ds_read_b128 v[4:7], v80
	v_or_b32_e32 v3, 8, v1
	v_lshlrev_b32_e32 v12, 11, v1
	v_mov_b32_e32 v13, v146
	v_lshl_add_u32 v10, v3, 7, v2
	v_lshl_add_u64 v[18:19], v[8:9], 0, v[12:13]
	ds_read_b128 v[12:15], v10
	s_waitcnt lgkmcnt(1)
	global_store_dwordx4 v[18:19], v[4:7], off
	s_mov_b64 s[6:7], 0
	s_nop 0
	v_lshlrev_b32_e32 v4, 11, v3
	v_mov_b32_e32 v5, v146
	v_or_b32_e32 v3, 16, v1
	v_lshl_add_u64 v[24:25], v[8:9], 0, v[4:5]
	v_lshl_add_u32 v21, v3, 7, v2
	v_or_b32_e32 v1, 24, v1
	ds_read_b128 v[4:7], v21
	s_waitcnt lgkmcnt(1)
	global_store_dwordx4 v[24:25], v[12:15], off
	v_lshl_add_u32 v23, v1, 7, v2
	v_lshlrev_b32_e32 v2, 11, v1
	v_lshlrev_b32_e32 v12, 11, v3
	v_mov_b32_e32 v13, v146
	v_lshl_add_u64 v[26:27], v[8:9], 0, v[12:13]
	ds_read_b128 v[12:15], v23
	v_mov_b32_e32 v3, v146
	v_lshl_add_u64 v[30:31], v[8:9], 0, v[2:3]
	s_waitcnt lgkmcnt(1)
	global_store_dwordx4 v[26:27], v[4:7], off
	v_cvt_pk_bf16_f32 v1, v11, s0
	s_waitcnt lgkmcnt(0)
	global_store_dwordx4 v[30:31], v[12:15], off
	ds_write_b16 v78, v1
	v_cvt_pk_bf16_f32 v1, v20, s0
	ds_write_b16 v78, v1 offset:64
	v_cvt_pk_bf16_f32 v1, v22, s0
	ds_write_b16 v78, v1 offset:128
	v_cvt_pk_bf16_f32 v1, v29, s0
	ds_write_b16 v78, v1 offset:192
	v_cvt_pk_bf16_f32 v1, v32, s0
	ds_write_b16 v78, v1 offset:256
	v_cvt_pk_bf16_f32 v1, v37, s0
	ds_write_b16 v78, v1 offset:320
	v_cvt_pk_bf16_f32 v1, v40, s0
	ds_write_b16 v78, v1 offset:384
	v_cvt_pk_bf16_f32 v1, v46, s0
	ds_write_b16 v78, v1 offset:448
	v_cvt_pk_bf16_f32 v1, v49, s0
	ds_write_b16 v78, v1 offset:1024
	v_cvt_pk_bf16_f32 v1, v55, s0
	ds_write_b16 v78, v1 offset:1088
	v_cvt_pk_bf16_f32 v1, v58, s0
	ds_write_b16 v78, v1 offset:1152
	v_cvt_pk_bf16_f32 v1, v63, s0
	ds_write_b16 v78, v1 offset:1216
	v_cvt_pk_bf16_f32 v1, v62, s0
	ds_write_b16 v78, v1 offset:1280
	v_cvt_pk_bf16_f32 v1, v64, s0
	ds_write_b16 v78, v1 offset:1344
	v_cvt_pk_bf16_f32 v1, v54, s0
	ds_write_b16 v78, v1 offset:1408
	v_cvt_pk_bf16_f32 v1, v56, s0
	ds_write_b16 v78, v1 offset:1472
	v_cvt_pk_bf16_f32 v1, v47, s0
	ds_write_b16 v78, v1 offset:2048
	v_cvt_pk_bf16_f32 v1, v50, s0
	ds_write_b16 v78, v1 offset:2112
	v_cvt_pk_bf16_f32 v1, v39, s0
	ds_write_b16 v78, v1 offset:2176
	v_cvt_pk_bf16_f32 v1, v42, s0
	ds_write_b16 v78, v1 offset:2240
	v_cvt_pk_bf16_f32 v1, v53, s0
	ds_write_b16 v78, v1 offset:2304
	v_cvt_pk_bf16_f32 v1, v48, s0
	ds_write_b16 v78, v1 offset:2368
	v_cvt_pk_bf16_f32 v1, v45, s0
	ds_write_b16 v78, v1 offset:2432
	v_cvt_pk_bf16_f32 v1, v41, s0
	ds_write_b16 v78, v1 offset:2496
	v_cvt_pk_bf16_f32 v1, v38, s0
	ds_write_b16 v78, v1 offset:3072
	v_cvt_pk_bf16_f32 v1, v34, s0
	ds_write_b16 v78, v1 offset:3136
	v_cvt_pk_bf16_f32 v1, v65, s0
	ds_write_b16 v78, v1 offset:3200
	v_cvt_pk_bf16_f32 v1, v79, s0
	ds_write_b16 v78, v1 offset:3264
	v_cvt_pk_bf16_f32 v1, v16, s0
	ds_write_b16 v78, v1 offset:3328
	v_cvt_pk_bf16_f32 v1, v75, s0
	ds_write_b16 v78, v1 offset:3392
	v_cvt_pk_bf16_f32 v1, v17, s0
	ds_write_b16 v78, v1 offset:3456
	v_cvt_pk_bf16_f32 v1, v61, s0
	ds_write_b16 v78, v1 offset:3520
	s_waitcnt lgkmcnt(0)
	ds_read_b128 v[2:5], v80
	ds_read_b128 v[6:9], v10
	ds_read_b128 v[10:13], v21
	ds_read_b128 v[14:17], v23
	s_waitcnt lgkmcnt(3)
	global_store_dwordx4 v[18:19], v[2:5], off offset:128
	s_waitcnt lgkmcnt(2)
	global_store_dwordx4 v[24:25], v[6:9], off offset:128
	s_waitcnt lgkmcnt(1)
	global_store_dwordx4 v[26:27], v[10:13], off offset:128
	s_waitcnt lgkmcnt(0)
	global_store_dwordx4 v[30:31], v[14:17], off offset:128
	s_barrier
